# v32 plus diff attention loop: K tile LDS-DMA issued half a tile earlier behind an extra mid-body barrier, end-of-body waits counted vmcnt(1)
# baseline (speedup 1.0000x reference)
; #define LAS __attribute__((address_space(3)))
; DI f32x16 mfma32(bf16x8 a, bf16x8 b, f32x16 c) { return __builtin_amdgcn_mfma_f32_32x32x16_bf16(a, b, c, 0, 0, 0); }
; DI f32x16 zero16() { f32x16 z; for (int i = 0; i < 16; ++i) z[i] = 0.f; return z; }
; template <int DQK, bool FOX>
; DI void attn_unit(const bf16_t* P, int pitch, int b, int qb, int qcol, int kcol, int vcol, bf16_t* Out, int opitch, int ocol, int gcol, const float* cum, lptr lds) {
;     ...
;     auto dma = [&](int kt, auto BUFC) {
;         constexpr int buf = decltype(BUFC)::value;
;         const size_t step = (size_t)kt * 64 * pitch;
; #pragma unroll
;         for (int i = 0; i < NKD; ++i) __builtin_amdgcn_global_load_lds((const unsigned*)(P + kgo[i] + step), (LAS unsigned*)(lds + OFF_K + buf * REG + (NKD * w + i) * 1024), 16, 0, 0);
; #pragma unroll
;         for (int i = 0; i < 2; ++i) __builtin_amdgcn_global_load_lds((const unsigned*)(P + vgo[i] + step), (LAS unsigned*)(lds + OFF_V + buf * REG + (2 * w + i) * 1024), 16, 0, 0);
;     };
;     auto body = [&](int it, auto BUFC) {
;         constexpr int buf = decltype(BUFC)::value;
;         const int kt = ntiles - 1 - it;
;         const bool more = (kt > 0);
;         if (more) { dma(kt - 1, std::integral_constant<int, 1 - buf>{}); if (FOX) { if (tid < 64) creg = -cum[(kt - 1) * 64 + tid] * LOG2E; } }
;         if (64 * kt <= q0 + 31) {
;             f32x16 pp[2];
; #pragma unroll
;             for (int t2 = 0; t2 < 2; ++t2) {
;                 if (FOX) {
; #pragma unroll
;                     for (int g = 0; g < 4; ++g) { const f32x4 ck = lld<f32x4>(lds, OFF_C + buf * 256 + cfo + (32 * t2 + 8 * g) * 4);
;                         pp[t2][4 * g] = ck[0]; pp[t2][4 * g + 1] = ck[1]; pp[t2][4 * g + 2] = ck[2]; pp[t2][4 * g + 3] = ck[3]; }
;                 } else pp[t2] = zero16();
; #pragma unroll
;                 for (int ks = 0; ks < NKS; ++ks) { const bf16x8 kf = lld<bf16x8>(lds + (OFF_K + buf * REG + 32 * t2 * KROWB), kx[ks]); pp[t2] = mfma32(kf, qf[ks], pp[t2]); } }
;     ...
;         asm volatile("s_waitcnt vmcnt(0)" ::: "memory");
;         __syncthreads();
.LBB0_532:
	v_mov_b32_e32 v133, v134
	s_barrier
	s_add_i32 s20, s14, 2
	s_cmp_ge_u32 s20, s15
	s_cbranch_scc1 .Lmy_dB_nok1
	s_add_i32 s20, s17, -2
	s_cmp_lt_i32 s20, 0
	s_cbranch_scc1 .Lmy_dB_nok1
	s_add_i32 m0, s10, 0x6000
	v_mad_u64_u32 v[158:159], s[26:27], s20, v210, v[116:117]
	s_nop 0
	global_load_lds_dwordx4 v[158:159], off
.Lmy_dB_nok1:
.LBB0_533:
	s_add_i32 s19, s14, 2
	s_cmp_ge_u32 s19, s15
	s_cbranch_scc1 .Lmy_eB_w0
	s_cmp_lt_i32 s17, 2
	s_cbranch_scc1 .Lmy_eB_w0
	s_waitcnt vmcnt(1) lgkmcnt(0)
	s_branch .Lmy_eB_j
.Lmy_eB_w0:
	s_waitcnt vmcnt(0) lgkmcnt(0)
.Lmy_eB_j:
	s_add_i32 s14, s14, 2
	s_add_i32 s17, s17, -2
	s_addk_i32 s18, 0xff80
	s_cmp_lt_u32 s14, s15
	s_barrier
	s_cbranch_scc0 .LBB0_551
.LBB0_534:
	s_add_i32 s19, s17, 1
	s_cmp_lt_i32 s19, 1
	s_cbranch_scc1 .LBB0_536
	s_cmp_lg_u32 s14, 0
	s_cbranch_scc1 .Lmy_dA_skipk
	v_mad_u64_u32 v[66:67], s[26:27], s17, v210, v[116:117]
	s_add_i32 m0, s10, 0x6000
	s_nop 0
	global_load_lds_dwordx4 v[66:67], off
.Lmy_dA_skipk:
	v_mad_u64_u32 v[66:67], s[26:27], s17, v210, v[118:119]
	s_add_i32 m0, s11, 0x8000
	s_nop 0
	global_load_lds_dwordx4 v[66:67], off
	v_mad_u64_u32 v[66:67], s[26:27], s17, v210, v[120:121]
	s_add_i32 m0, s11, 0x8400
	s_nop 0
	global_load_lds_dwordx4 v[66:67], off
.LBB0_536:
	s_sub_i32 s19, s18, 63
	s_cmp_gt_i32 s19, s16
	s_cbranch_scc1 .LBB0_542
	ds_read_b128 v[212:215], v123
	ds_read_b128 v[216:219], v124
	ds_read_b128 v[220:223], v125
	ds_read_b128 v[224:227], v126
	ds_read_b128 v[228:231], v123 offset:4096
	ds_read_b128 v[232:235], v124 offset:4096
	ds_read_b128 v[236:239], v125 offset:4096
	ds_read_b128 v[240:243], v126 offset:4096
	s_waitcnt lgkmcnt(7)
	v_mfma_f32_32x32x16_bf16 v[82:97], v[212:215], v[106:109], 0
	s_waitcnt lgkmcnt(6)
	v_mfma_f32_32x32x16_bf16 v[82:97], v[216:219], v[98:101], v[82:97]
	s_waitcnt lgkmcnt(5)
	v_mfma_f32_32x32x16_bf16 v[82:97], v[220:223], v[102:105], v[82:97]
	s_waitcnt lgkmcnt(4)
	v_mfma_f32_32x32x16_bf16 v[82:97], v[224:227], v[110:113], v[82:97]
	s_waitcnt lgkmcnt(3)
	v_mfma_f32_32x32x16_bf16 v[66:81], v[228:231], v[106:109], 0
	s_waitcnt lgkmcnt(2)
	v_mfma_f32_32x32x16_bf16 v[66:81], v[232:235], v[98:101], v[66:81]
	s_waitcnt lgkmcnt(1)
	v_mfma_f32_32x32x16_bf16 v[66:81], v[236:239], v[102:105], v[66:81]
	s_waitcnt lgkmcnt(0)
	v_mfma_f32_32x32x16_bf16 v[66:81], v[240:243], v[110:113], v[66:81]
	s_barrier
	s_sub_i32 s19, s15, s14
	s_add_i32 s19, s19, -3
	s_cmp_lt_i32 s19, 0
	s_cbranch_scc1 .Lmy_dA_nok0
	s_mov_b32 m0, s10
	v_mad_u64_u32 v[158:159], s[26:27], s19, v210, v[116:117]
	s_nop 0
	global_load_lds_dwordx4 v[158:159], off
; DI int crow(int i, int h) { return (i & 3) + 8 * (i >> 2) + 4 * h; }
; DI f32x16 mfma32(bf16x8 a, bf16x8 b, f32x16 c) { return __builtin_amdgcn_mfma_f32_32x32x16_bf16(a, b, c, 0, 0, 0); }
; DI s16x4 vtr(lptr p) { return __builtin_bit_cast(s16x4, __builtin_amdgcn_ds_read_tr16_b64_v4i16((LAS s16x4*)p)); }
; template <int DQK, bool FOX>
; DI void attn_unit(const bf16_t* P, int pitch, int b, int qb, int qcol, int kcol, int vcol, bf16_t* Out, int opitch, int ocol, int gcol, const float* cum, lptr lds) {
;     ...
;             const bool diag = (64 * kt + 63 > q0);
;             if (diag) {
; #pragma unroll
;                 for (int t2 = 0; t2 < 2; ++t2)
; #pragma unroll
;                     for (int i = 0; i < 16; ++i) { const int key = 64 * kt + 32 * t2 + crow(i, h); if (key > q0 + r) pp[t2][i] = NEGBIG; }
;             }
;             float mx = NEGBIG;
; #pragma unroll
;             for (int t2 = 0; t2 < 2; ++t2)
; #pragma unroll
;                 for (int i = 0; i < 16; ++i) mx = fmaxf(mx, pp[t2][i]);
;             mx = fmaxf(mx, shx(mx, 32));
;             const float m_new = fmaxf(m_run, mx);
;             const float alpha = __builtin_amdgcn_exp2f(m_run - m_new);
;             const bool changed = __builtin_amdgcn_ballot_w64(m_new > m_run) != 0ull;
;             m_run = m_new;
;             float ls = 0.f;
; #pragma unroll
;             for (int t2 = 0; t2 < 2; ++t2)
; #pragma unroll
;                 for (int i = 0; i < 16; ++i) { const float e = __builtin_amdgcn_exp2f(pp[t2][i] - m_new); pp[t2][i] = e; ls += e; }
;             l_run = l_run * alpha + ls;
;             if (changed) {
; #pragma unroll
;                 for (int d = 0; d < 4; ++d) O[d] *= alpha;
;             }
;             bf16x8 pf[4];
; #pragma unroll
;             for (int s = 0; s < 4; ++s) pf[s] = pack8(pp[s >> 1], s & 1);
; #pragma unroll
;             for (int d = 0; d < 4; ++d)
; #pragma unroll
;                 for (int s = 0; s < 4; ++s) {
;                     const s16x4 lo = vtr(lds + (OFF_V + buf * REG + (16 * s) * 256) + vx[d]), hi = vtr(lds + (OFF_V + buf * REG + (16 * s + 8) * 256) + vx[d]);
;                     const bf16x8 vf = __builtin_shufflevector(lo, hi, 0, 1, 2, 3, 4, 5, 6, 7);
;                     O[d] = mfma32(vf, pf[s], O[d]);
;                 }
.Lmy_dA_nok0:
	ds_read_b64_tr_b16 v[212:213], v127 offset:8192
	ds_read_b64_tr_b16 v[214:215], v127 offset:10240
	ds_read_b64_tr_b16 v[216:217], v127 offset:12288
	ds_read_b64_tr_b16 v[218:219], v127 offset:14336
	ds_read_b64_tr_b16 v[220:221], v127 offset:16384
	ds_read_b64_tr_b16 v[222:223], v127 offset:18432
	ds_read_b64_tr_b16 v[224:225], v127 offset:20480
	ds_read_b64_tr_b16 v[226:227], v127 offset:22528
	ds_read_b64_tr_b16 v[228:229], v128 offset:8192
	ds_read_b64_tr_b16 v[230:231], v128 offset:10240
	ds_read_b64_tr_b16 v[232:233], v128 offset:12288
	ds_read_b64_tr_b16 v[234:235], v128 offset:14336
	ds_read_b64_tr_b16 v[236:237], v128 offset:16384
	ds_read_b64_tr_b16 v[238:239], v128 offset:18432
	ds_read_b64_tr_b16 v[240:241], v128 offset:20480
	ds_read_b64_tr_b16 v[242:243], v128 offset:22528
	ds_read_b64_tr_b16 v[244:245], v129 offset:8192
	ds_read_b64_tr_b16 v[246:247], v129 offset:10240
	s_cmp_le_i32 s18, s3
	s_cbranch_scc1 .LBB0_539
	v_add_u32_e32 v0, s18, v122
	v_subrev_u32_e32 v134, 63, v0
	v_cmp_lt_i32_e32 vcc, v134, v131
	s_nop 1
	v_cndmask_b32_e32 v83, v205, v83, vcc
	v_cmp_le_i32_e32 vcc, v134, v131
	v_subrev_u32_e32 v134, 61, v0
	s_nop 0
	v_cndmask_b32_e32 v82, v205, v82, vcc
	v_cmp_le_i32_e32 vcc, v134, v131
	v_subrev_u32_e32 v134, 60, v0
	s_nop 0
	v_cndmask_b32_e32 v84, v205, v84, vcc
	v_cmp_le_i32_e32 vcc, v134, v131
	v_subrev_u32_e32 v134, 55, v0
	s_nop 0
	v_cndmask_b32_e32 v85, v205, v85, vcc
	v_cmp_le_i32_e32 vcc, v134, v131
	v_subrev_u32_e32 v134, 54, v0
	s_nop 0
	v_cndmask_b32_e32 v86, v205, v86, vcc
	v_cmp_le_i32_e32 vcc, v134, v131
	v_subrev_u32_e32 v134, 53, v0
	s_nop 0
	v_cndmask_b32_e32 v87, v205, v87, vcc
	v_cmp_le_i32_e32 vcc, v134, v131
	v_subrev_u32_e32 v134, 52, v0
	s_nop 0
	v_cndmask_b32_e32 v88, v205, v88, vcc
	v_cmp_le_i32_e32 vcc, v134, v131
	v_subrev_u32_e32 v134, 47, v0
	s_nop 0
	v_cndmask_b32_e32 v89, v205, v89, vcc
	v_cmp_le_i32_e32 vcc, v134, v131
	v_subrev_u32_e32 v134, 46, v0
	s_nop 0
	v_cndmask_b32_e32 v90, v205, v90, vcc
	v_cmp_le_i32_e32 vcc, v134, v131
	v_subrev_u32_e32 v134, 45, v0
	s_nop 0
	v_cndmask_b32_e32 v91, v205, v91, vcc
	v_cmp_le_i32_e32 vcc, v134, v131
	v_subrev_u32_e32 v134, 44, v0
	s_nop 0
	v_cndmask_b32_e32 v92, v205, v92, vcc
	v_cmp_le_i32_e32 vcc, v134, v131
	v_subrev_u32_e32 v134, 39, v0
	s_nop 0
	v_cndmask_b32_e32 v93, v205, v93, vcc
	v_cmp_le_i32_e32 vcc, v134, v131
	v_subrev_u32_e32 v134, 38, v0
	s_nop 0
	v_cndmask_b32_e32 v94, v205, v94, vcc
	v_cmp_le_i32_e32 vcc, v134, v131
	v_subrev_u32_e32 v134, 37, v0
	s_nop 0
	v_cndmask_b32_e32 v95, v205, v95, vcc
	v_cmp_le_i32_e32 vcc, v134, v131
	v_subrev_u32_e32 v134, 36, v0
	s_nop 0
	v_cndmask_b32_e32 v96, v205, v96, vcc
	v_cmp_le_i32_e32 vcc, v134, v131
	v_subrev_u32_e32 v134, 31, v0
	s_nop 0
	v_cndmask_b32_e32 v97, v205, v97, vcc
	v_cmp_le_i32_e32 vcc, v134, v131
	v_subrev_u32_e32 v134, 30, v0
	s_nop 0
	v_cndmask_b32_e32 v66, v205, v66, vcc
	v_cmp_le_i32_e32 vcc, v134, v131
	v_subrev_u32_e32 v134, 29, v0
	s_nop 0
	v_cndmask_b32_e32 v67, v205, v67, vcc
	v_cmp_le_i32_e32 vcc, v134, v131
	v_subrev_u32_e32 v134, 28, v0
	s_nop 0
	v_cndmask_b32_e32 v68, v205, v68, vcc
	v_cmp_le_i32_e32 vcc, v134, v131
	v_subrev_u32_e32 v134, 23, v0
	s_nop 0
	v_cndmask_b32_e32 v69, v205, v69, vcc
	v_cmp_le_i32_e32 vcc, v134, v131
	v_subrev_u32_e32 v134, 22, v0
	s_nop 0
	v_cndmask_b32_e32 v70, v205, v70, vcc
	v_cmp_le_i32_e32 vcc, v134, v131
	v_subrev_u32_e32 v134, 21, v0
	s_nop 0
	v_cndmask_b32_e32 v71, v205, v71, vcc
	v_cmp_le_i32_e32 vcc, v134, v131
	v_subrev_u32_e32 v134, 20, v0
	s_nop 0
	v_cndmask_b32_e32 v72, v205, v72, vcc
	v_cmp_le_i32_e32 vcc, v134, v131
	v_add_u32_e32 v134, -15, v0
	s_nop 0
	v_cndmask_b32_e32 v73, v205, v73, vcc
	v_cmp_le_i32_e32 vcc, v134, v131
	v_add_u32_e32 v134, -14, v0
	s_nop 0
	v_cndmask_b32_e32 v74, v205, v74, vcc
	v_cmp_le_i32_e32 vcc, v134, v131
	v_add_u32_e32 v134, -13, v0
	s_nop 0
	v_cndmask_b32_e32 v75, v205, v75, vcc
	v_cmp_le_i32_e32 vcc, v134, v131
	v_add_u32_e32 v134, -12, v0
	s_nop 0
	v_cndmask_b32_e32 v76, v205, v76, vcc
	v_cmp_le_i32_e32 vcc, v134, v131
	v_add_u32_e32 v134, -7, v0
	s_nop 0
	v_cndmask_b32_e32 v77, v205, v77, vcc
	v_cmp_le_i32_e32 vcc, v134, v131
	v_add_u32_e32 v134, -6, v0
	s_nop 0
	v_cndmask_b32_e32 v78, v205, v78, vcc
	v_cmp_le_i32_e32 vcc, v134, v131
	v_add_u32_e32 v134, -5, v0
	v_add_u32_e32 v0, -4, v0
	v_cndmask_b32_e32 v79, v205, v79, vcc
	v_cmp_le_i32_e32 vcc, v134, v131
	s_nop 1
	v_cndmask_b32_e32 v80, v205, v80, vcc
	v_cmp_le_i32_e32 vcc, v0, v131
	s_nop 1
	v_cndmask_b32_e32 v81, v205, v81, vcc

; #define LAS __attribute__((address_space(3)))
; template <int DQK, bool FOX>
; DI void attn_unit(const bf16_t* P, int pitch, int b, int qb, int qcol, int kcol, int vcol, bf16_t* Out, int opitch, int ocol, int gcol, const float* cum, lptr lds) {
;     ...
;     auto dma = [&](int kt, auto BUFC) {
;         constexpr int buf = decltype(BUFC)::value;
;         const size_t step = (size_t)kt * 64 * pitch;
; #pragma unroll
;         for (int i = 0; i < NKD; ++i) __builtin_amdgcn_global_load_lds((const unsigned*)(P + kgo[i] + step), (LAS unsigned*)(lds + OFF_K + buf * REG + (NKD * w + i) * 1024), 16, 0, 0);
; #pragma unroll
;         for (int i = 0; i < 2; ++i) __builtin_amdgcn_global_load_lds((const unsigned*)(P + vgo[i] + step), (LAS unsigned*)(lds + OFF_V + buf * REG + (2 * w + i) * 1024), 16, 0, 0);
;     };
;     ...
;         if (FOX) { if (more && tid < 64) lst<float>(lds, OFF_C + (1 - buf) * 256 + tid * 4, creg); }
;         asm volatile("s_waitcnt vmcnt(0)" ::: "memory");
;         __syncthreads();
.LBB0_542:
	v_mov_b32_e32 v134, v133
	s_barrier
	s_sub_i32 s19, s15, s14
	s_add_i32 s19, s19, -3
	s_cmp_lt_i32 s19, 0
	s_cbranch_scc1 .Lmy_dA_nok1
	s_mov_b32 m0, s10
	v_mad_u64_u32 v[158:159], s[26:27], s19, v210, v[116:117]
	s_nop 0
	global_load_lds_dwordx4 v[158:159], off
.Lmy_dA_nok1:
.LBB0_543:
	s_sub_i32 s19, s15, s14
	s_cmp_lt_i32 s19, 3
	s_cbranch_scc1 .Lmy_eA_w0
	s_waitcnt vmcnt(1) lgkmcnt(0)
	s_branch .Lmy_eA_j

; #define LAS __attribute__((address_space(3)))
; DI int crow(int i, int h) { return (i & 3) + 8 * (i >> 2) + 4 * h; }
; DI f32x16 mfma32(bf16x8 a, bf16x8 b, f32x16 c) { return __builtin_amdgcn_mfma_f32_32x32x16_bf16(a, b, c, 0, 0, 0); }
; DI f32x16 zero16() { f32x16 z; for (int i = 0; i < 16; ++i) z[i] = 0.f; return z; }
; template <int DQK, bool FOX>
; DI void attn_unit(const bf16_t* P, int pitch, int b, int qb, int qcol, int kcol, int vcol, bf16_t* Out, int opitch, int ocol, int gcol, const float* cum, lptr lds) {
;     ...
;         for (int i = 0; i < NKD; ++i) __builtin_amdgcn_global_load_lds((const unsigned*)(P + kgo[i] + step), (LAS unsigned*)(lds + OFF_K + buf * REG + (NKD * w + i) * 1024), 16, 0, 0);
; #pragma unroll
;         for (int i = 0; i < 2; ++i) __builtin_amdgcn_global_load_lds((const unsigned*)(P + vgo[i] + step), (LAS unsigned*)(lds + OFF_V + buf * REG + (2 * w + i) * 1024), 16, 0, 0);
;     };
;     auto body = [&](int it, auto BUFC) {
;         constexpr int buf = decltype(BUFC)::value;
;         const int kt = ntiles - 1 - it;
;         const bool more = (kt > 0);
;         if (more) { dma(kt - 1, std::integral_constant<int, 1 - buf>{}); if (FOX) { if (tid < 64) creg = -cum[(kt - 1) * 64 + tid] * LOG2E; } }
;         if (64 * kt <= q0 + 31) {
;             f32x16 pp[2];
; #pragma unroll
;             for (int t2 = 0; t2 < 2; ++t2) {
;                 if (FOX) {
; #pragma unroll
;                     for (int g = 0; g < 4; ++g) { const f32x4 ck = lld<f32x4>(lds, OFF_C + buf * 256 + cfo + (32 * t2 + 8 * g) * 4);
;                         pp[t2][4 * g] = ck[0]; pp[t2][4 * g + 1] = ck[1]; pp[t2][4 * g + 2] = ck[2]; pp[t2][4 * g + 3] = ck[3]; }
;                 } else pp[t2] = zero16();
; #pragma unroll
;                 for (int ks = 0; ks < NKS; ++ks) { const bf16x8 kf = lld<bf16x8>(lds + (OFF_K + buf * REG + 32 * t2 * KROWB), kx[ks]); pp[t2] = mfma32(kf, qf[ks], pp[t2]); } }
;             const bool diag = (64 * kt + 63 > q0);
;             if (diag) {
; #pragma unroll
;                 for (int t2 = 0; t2 < 2; ++t2)
; #pragma unroll
;                     for (int i = 0; i < 16; ++i) { const int key = 64 * kt + 32 * t2 + crow(i, h); if (key > q0 + r) pp[t2][i] = NEGBIG; }
.Lmy_eA_j:
	s_xor_b32 s19, s14, -2
	s_add_i32 s19, s19, s15
	s_cmp_lt_i32 s19, 1
	s_barrier
	s_cbranch_scc1 .LBB0_545
	s_add_i32 s20, s19, -1
	v_mad_u64_u32 v[66:67], s[26:27], s20, v210, v[118:119]
	s_mov_b32 m0, s12
	s_nop 0
	global_load_lds_dwordx4 v[66:67], off
	v_mad_u64_u32 v[66:67], s[26:27], s20, v210, v[120:121]
	s_mov_b32 m0, s13
	s_nop 0
	global_load_lds_dwordx4 v[66:67], off
.LBB0_545:
	s_lshl_b32 s19, s19, 6
	s_cmp_gt_i32 s19, s16
	s_cbranch_scc1 .LBB0_532
	ds_read_b128 v[212:215], v123 offset:24576
	ds_read_b128 v[216:219], v124 offset:24576
	ds_read_b128 v[220:223], v125 offset:24576
	ds_read_b128 v[224:227], v126 offset:24576
	ds_read_b128 v[228:231], v123 offset:28672
	ds_read_b128 v[232:235], v124 offset:28672
	ds_read_b128 v[236:239], v125 offset:28672
	ds_read_b128 v[240:243], v126 offset:28672
	s_waitcnt lgkmcnt(7)
	v_mfma_f32_32x32x16_bf16 v[82:97], v[212:215], v[106:109], 0
	s_waitcnt lgkmcnt(6)
	v_mfma_f32_32x32x16_bf16 v[82:97], v[216:219], v[98:101], v[82:97]
	s_waitcnt lgkmcnt(5)
	v_mfma_f32_32x32x16_bf16 v[82:97], v[220:223], v[102:105], v[82:97]
	s_waitcnt lgkmcnt(4)
	v_mfma_f32_32x32x16_bf16 v[82:97], v[224:227], v[110:113], v[82:97]
	s_waitcnt lgkmcnt(3)
	v_mfma_f32_32x32x16_bf16 v[66:81], v[228:231], v[106:109], 0
	s_waitcnt lgkmcnt(2)
	v_mfma_f32_32x32x16_bf16 v[66:81], v[232:235], v[98:101], v[66:81]
	s_waitcnt lgkmcnt(1)
	v_mfma_f32_32x32x16_bf16 v[66:81], v[236:239], v[102:105], v[66:81]
	s_waitcnt lgkmcnt(0)
	v_mfma_f32_32x32x16_bf16 v[66:81], v[240:243], v[110:113], v[66:81]
	s_barrier
	s_add_i32 s20, s14, 2
	s_cmp_ge_u32 s20, s15
	s_cbranch_scc1 .Lmy_dB_nok0
	s_add_i32 s20, s17, -2
	s_cmp_lt_i32 s20, 0
	s_cbranch_scc1 .Lmy_dB_nok0
	s_add_i32 m0, s10, 0x6000
	v_mad_u64_u32 v[158:159], s[26:27], s20, v210, v[116:117]
	s_nop 0
	global_load_lds_dwordx4 v[158:159], off
.Lmy_dB_nok0:
	ds_read_b64_tr_b16 v[212:213], v127 offset:32768
	ds_read_b64_tr_b16 v[214:215], v127 offset:34816
	ds_read_b64_tr_b16 v[216:217], v127 offset:36864
	ds_read_b64_tr_b16 v[218:219], v127 offset:38912
	ds_read_b64_tr_b16 v[220:221], v127 offset:40960
	ds_read_b64_tr_b16 v[222:223], v127 offset:43008
	ds_read_b64_tr_b16 v[224:225], v127 offset:45056
	ds_read_b64_tr_b16 v[226:227], v127 offset:47104
	ds_read_b64_tr_b16 v[228:229], v128 offset:32768
	ds_read_b64_tr_b16 v[230:231], v128 offset:34816
	ds_read_b64_tr_b16 v[232:233], v128 offset:36864
	ds_read_b64_tr_b16 v[234:235], v128 offset:38912
	ds_read_b64_tr_b16 v[236:237], v128 offset:40960
	ds_read_b64_tr_b16 v[238:239], v128 offset:43008
	ds_read_b64_tr_b16 v[240:241], v128 offset:45056
	ds_read_b64_tr_b16 v[242:243], v128 offset:47104
	ds_read_b64_tr_b16 v[244:245], v129 offset:32768
	ds_read_b64_tr_b16 v[246:247], v129 offset:34816
	s_or_b32 s20, s19, 63
	s_cmp_le_i32 s20, s3
	s_cbranch_scc1 .LBB0_548
	v_or_b32_e32 v0, s19, v122
	v_cmp_lt_i32_e32 vcc, v0, v131
	v_or_b32_e32 v133, 2, v0
	s_nop 0
	v_cndmask_b32_e32 v83, v205, v83, vcc
	v_cmp_le_i32_e32 vcc, v0, v131
	s_nop 1
	v_cndmask_b32_e32 v82, v205, v82, vcc
	v_cmp_le_i32_e32 vcc, v133, v131
	v_or_b32_e32 v133, 3, v0
	s_nop 0
	v_cndmask_b32_e32 v84, v205, v84, vcc
	v_cmp_le_i32_e32 vcc, v133, v131
	v_or_b32_e32 v133, 8, v0
	s_nop 0
	v_cndmask_b32_e32 v85, v205, v85, vcc
	v_cmp_le_i32_e32 vcc, v133, v131
	v_or_b32_e32 v133, 9, v0
	s_nop 0
	v_cndmask_b32_e32 v86, v205, v86, vcc
	v_cmp_le_i32_e32 vcc, v133, v131
	v_or_b32_e32 v133, 10, v0
	s_nop 0
	v_cndmask_b32_e32 v87, v205, v87, vcc
	v_cmp_le_i32_e32 vcc, v133, v131
	v_or_b32_e32 v133, 11, v0
	s_nop 0
	v_cndmask_b32_e32 v88, v205, v88, vcc
	v_cmp_le_i32_e32 vcc, v133, v131
	v_or_b32_e32 v133, 16, v0
	s_nop 0
	v_cndmask_b32_e32 v89, v205, v89, vcc
	v_cmp_le_i32_e32 vcc, v133, v131
	v_or_b32_e32 v133, 17, v0
	s_nop 0
	v_cndmask_b32_e32 v90, v205, v90, vcc
	v_cmp_le_i32_e32 vcc, v133, v131
	v_or_b32_e32 v133, 18, v0
	s_nop 0
	v_cndmask_b32_e32 v91, v205, v91, vcc
	v_cmp_le_i32_e32 vcc, v133, v131
	v_or_b32_e32 v133, 19, v0
	s_nop 0
	v_cndmask_b32_e32 v92, v205, v92, vcc
	v_cmp_le_i32_e32 vcc, v133, v131
	v_or_b32_e32 v133, 24, v0
	s_nop 0
	v_cndmask_b32_e32 v93, v205, v93, vcc
	v_cmp_le_i32_e32 vcc, v133, v131
	v_or_b32_e32 v133, 25, v0
	s_nop 0
	v_cndmask_b32_e32 v94, v205, v94, vcc
	v_cmp_le_i32_e32 vcc, v133, v131
	v_or_b32_e32 v133, 26, v0
	s_nop 0
	v_cndmask_b32_e32 v95, v205, v95, vcc
	v_cmp_le_i32_e32 vcc, v133, v131
	v_or_b32_e32 v133, 27, v0
	s_nop 0
	v_cndmask_b32_e32 v96, v205, v96, vcc
	v_cmp_le_i32_e32 vcc, v133, v131
	v_or_b32_e32 v133, 32, v0
	s_nop 0
	v_cndmask_b32_e32 v97, v205, v97, vcc
	v_cmp_le_i32_e32 vcc, v133, v131
	v_or_b32_e32 v133, 33, v0
	s_nop 0
	v_cndmask_b32_e32 v66, v205, v66, vcc
	v_cmp_le_i32_e32 vcc, v133, v131
	v_or_b32_e32 v133, 34, v0
	s_nop 0
	v_cndmask_b32_e32 v67, v205, v67, vcc
	v_cmp_le_i32_e32 vcc, v133, v131
	v_or_b32_e32 v133, 35, v0
	s_nop 0
	v_cndmask_b32_e32 v68, v205, v68, vcc
	v_cmp_le_i32_e32 vcc, v133, v131
	v_or_b32_e32 v133, 40, v0
	s_nop 0
	v_cndmask_b32_e32 v69, v205, v69, vcc
	v_cmp_le_i32_e32 vcc, v133, v131
	v_or_b32_e32 v133, 41, v0
	s_nop 0
	v_cndmask_b32_e32 v70, v205, v70, vcc
	v_cmp_le_i32_e32 vcc, v133, v131
	v_or_b32_e32 v133, 42, v0
	s_nop 0
	v_cndmask_b32_e32 v71, v205, v71, vcc
	v_cmp_le_i32_e32 vcc, v133, v131
	v_or_b32_e32 v133, 43, v0
	s_nop 0
	v_cndmask_b32_e32 v72, v205, v72, vcc
	v_cmp_le_i32_e32 vcc, v133, v131
	v_or_b32_e32 v133, 48, v0
	s_nop 0
	v_cndmask_b32_e32 v73, v205, v73, vcc
	v_cmp_le_i32_e32 vcc, v133, v131
	v_or_b32_e32 v133, 49, v0
	s_nop 0
	v_cndmask_b32_e32 v74, v205, v74, vcc
	v_cmp_le_i32_e32 vcc, v133, v131
	v_or_b32_e32 v133, 50, v0
	s_nop 0
	v_cndmask_b32_e32 v75, v205, v75, vcc
	v_cmp_le_i32_e32 vcc, v133, v131
	v_or_b32_e32 v133, 51, v0
	s_nop 0
	v_cndmask_b32_e32 v76, v205, v76, vcc
	v_cmp_le_i32_e32 vcc, v133, v131
	v_or_b32_e32 v133, 56, v0
	s_nop 0
	v_cndmask_b32_e32 v77, v205, v77, vcc
	v_cmp_le_i32_e32 vcc, v133, v131
	v_or_b32_e32 v133, 57, v0
	s_nop 0
	v_cndmask_b32_e32 v78, v205, v78, vcc
	v_cmp_le_i32_e32 vcc, v133, v131
	v_or_b32_e32 v133, 58, v0
	v_or_b32_e32 v0, 59, v0
	v_cndmask_b32_e32 v79, v205, v79, vcc
	v_cmp_le_i32_e32 vcc, v133, v131
	s_nop 1
	v_cndmask_b32_e32 v80, v205, v80, vcc
	v_cmp_le_i32_e32 vcc, v0, v131
	s_nop 1
	v_cndmask_b32_e32 v81, v205, v81, vcc
